# LRU prefetch split 4 pieces in conv / 8 in gate stage (was 5/7), rest as the previous best
# speedup vs baseline: 1.0003x; 1.0003x over previous
; #define LAS __attribute__((address_space(3)))
; __device__ __forceinline__ unsigned cvt_pk_bf16(float lo, float hi) { unsigned r; asm("v_cvt_pk_bf16_f32 %0, %1, %2" : "=v"(r) : "v"(lo), "v"(hi)); return r; }
; __device__ __forceinline__ void lru_item(const Args& a, LAS unsigned char* lds, bool sample, int b, int head, int q, int tid, int lane, int wave) {
;     ...
; #pragma unroll
;             for (int rr = 0; rr < 8; ++rr) {
;                 const f32x4 xc = cb + cw0 * xin[rr] + cw1 * xin[rr + 1] + cw2 * xin[rr + 2] + cw3 * xin[rr + 3];
;                 u32x2 w; w.x = cvt_pk_bf16(xc[0], xc[1]); w.y = cvt_pk_bf16(xc[2], xc[3]);
;                 *(LAS u32x2*)(XC + (r0 + rr) * XC_PITCH + 8 * cq) = w;
;                 if ((cq >> 2) == q) *(LAS f32x4*)(XCF + (r0 + rr) * 16 + 4 * (cq & 3)) = xc;
;             }
;             const u32x4 gw = ggn;
;             if (chk < 7) {
;                 const float* p = XL + (size_t)(R0 + 256 + r0 - 3) * DH + cch;
; #pragma unroll
;                 for (int i = 0; i < 11; ++i) xin[i] = *(const f32x4*)(p + (size_t)i * DH);
;                 ggn = *(const u32x4*)(GG + (size_t)(R0 + 256 + er) * DH + ch0 + 8 * eh);
;             }
.LBB0_672:
	v_mov_b32_e32 v228, 0x1000
	v_mov_b32_e32 v229, 0
	v_add_u32_e32 v224, s30, v182
	v_ashrrev_i32_e32 v225, 31, v224
	v_lshlrev_b64 v[224:225], 12, v[224:225]
	v_lshl_add_u64 v[224:225], v[110:111], 0, v[224:225]
	v_pk_fma_f32 v[50:51], v[32:33], v[88:89], v[36:37]
	v_pk_fma_f32 v[52:53], v[30:31], v[86:87], v[34:35]
	v_pk_fma_f32 v[50:51], v[28:29], v[84:85], v[50:51]
	v_pk_fma_f32 v[52:53], v[26:27], v[82:83], v[52:53]
	v_pk_fma_f32 v[50:51], v[24:25], v[80:81], v[50:51]
	v_pk_fma_f32 v[86:87], v[22:23], v[78:79], v[52:53]
	v_pk_fma_f32 v[52:53], v[20:21], v[72:73], v[50:51]
	v_pk_fma_f32 v[50:51], v[18:19], v[70:71], v[86:87]
	v_cvt_pk_bf16_f32 v87, v52, v53
	s_nop 0
	v_cvt_pk_bf16_f32 v86, v50, v51
	ds_write_b64 v175, v[86:87]
	s_and_saveexec_b64 s[36:37], s[8:9]
	v_add_u32_e32 v86, v137, v138
	ds_write_b128 v86, v[50:53] offset:36864
	s_or_b64 exec, exec, s[36:37]
	global_load_dwordx4 v[86:89], v[224:225], off
	v_lshl_add_u64 v[224:225], v[224:225], 0, v[228:229]
	v_pk_fma_f32 v[50:51], v[32:33], v[84:85], v[36:37]
	v_pk_fma_f32 v[52:53], v[30:31], v[82:83], v[34:35]
	v_pk_fma_f32 v[50:51], v[28:29], v[80:81], v[50:51]
	v_pk_fma_f32 v[52:53], v[26:27], v[78:79], v[52:53]
	v_pk_fma_f32 v[50:51], v[24:25], v[72:73], v[50:51]
	v_pk_fma_f32 v[82:83], v[22:23], v[70:71], v[52:53]
	v_pk_fma_f32 v[52:53], v[20:21], v[68:69], v[50:51]
	v_pk_fma_f32 v[50:51], v[18:19], v[66:67], v[82:83]
	v_cvt_pk_bf16_f32 v83, v52, v53
	s_nop 0
	v_cvt_pk_bf16_f32 v82, v50, v51
	ds_write_b64 v176, v[82:83]
	s_and_saveexec_b64 s[36:37], s[8:9]
	v_add_u32_e32 v82, v137, v148
	ds_write_b128 v82, v[50:53] offset:36864
	s_or_b64 exec, exec, s[36:37]
	global_load_dwordx4 v[82:85], v[224:225], off
	v_lshl_add_u64 v[224:225], v[224:225], 0, v[228:229]
	v_pk_fma_f32 v[50:51], v[32:33], v[80:81], v[36:37]
	v_pk_fma_f32 v[52:53], v[30:31], v[78:79], v[34:35]
	v_pk_fma_f32 v[50:51], v[28:29], v[72:73], v[50:51]
	v_pk_fma_f32 v[52:53], v[26:27], v[70:71], v[52:53]
	v_pk_fma_f32 v[50:51], v[24:25], v[68:69], v[50:51]
	v_pk_fma_f32 v[78:79], v[22:23], v[66:67], v[52:53]
	v_pk_fma_f32 v[52:53], v[20:21], v[64:65], v[50:51]
	v_pk_fma_f32 v[50:51], v[18:19], v[62:63], v[78:79]
	v_cvt_pk_bf16_f32 v79, v52, v53
	s_nop 0
	v_cvt_pk_bf16_f32 v78, v50, v51
	ds_write_b64 v176, v[78:79] offset:144
	s_and_saveexec_b64 s[36:37], s[8:9]
	v_add_u32_e32 v78, v137, v149
	ds_write_b128 v78, v[50:53] offset:36864
	s_or_b64 exec, exec, s[36:37]
	global_load_dwordx4 v[78:81], v[224:225], off
	v_lshl_add_u64 v[224:225], v[224:225], 0, v[228:229]
	v_pk_fma_f32 v[50:51], v[32:33], v[72:73], v[36:37]
	v_pk_fma_f32 v[52:53], v[30:31], v[70:71], v[34:35]
	v_pk_fma_f32 v[50:51], v[28:29], v[68:69], v[50:51]
	v_pk_fma_f32 v[52:53], v[26:27], v[66:67], v[52:53]
	v_pk_fma_f32 v[50:51], v[24:25], v[64:65], v[50:51]
	v_pk_fma_f32 v[70:71], v[22:23], v[62:63], v[52:53]
	v_pk_fma_f32 v[52:53], v[20:21], v[60:61], v[50:51]
	v_pk_fma_f32 v[50:51], v[18:19], v[58:59], v[70:71]
	v_cvt_pk_bf16_f32 v71, v52, v53
	s_nop 0
	v_cvt_pk_bf16_f32 v70, v50, v51
	ds_write_b64 v176, v[70:71] offset:288
	s_and_saveexec_b64 s[36:37], s[8:9]
	v_add_u32_e32 v70, v137, v150
	ds_write_b128 v70, v[50:53] offset:36864
	s_or_b64 exec, exec, s[36:37]
	global_load_dwordx4 v[70:73], v[224:225], off
	v_lshl_add_u64 v[224:225], v[224:225], 0, v[228:229]
	v_pk_fma_f32 v[50:51], v[32:33], v[68:69], v[36:37]
	v_pk_fma_f32 v[52:53], v[30:31], v[66:67], v[34:35]
	v_pk_fma_f32 v[50:51], v[28:29], v[64:65], v[50:51]
	v_pk_fma_f32 v[52:53], v[26:27], v[62:63], v[52:53]
	v_pk_fma_f32 v[50:51], v[24:25], v[60:61], v[50:51]
	v_pk_fma_f32 v[66:67], v[22:23], v[58:59], v[52:53]
	v_pk_fma_f32 v[52:53], v[20:21], v[40:41], v[50:51]
	v_pk_fma_f32 v[50:51], v[18:19], v[38:39], v[66:67]
	v_cvt_pk_bf16_f32 v67, v52, v53
	s_nop 0
	v_cvt_pk_bf16_f32 v66, v50, v51
	ds_write_b64 v176, v[66:67] offset:432
	s_and_saveexec_b64 s[36:37], s[8:9]
	v_add_u32_e32 v66, v137, v151
	ds_write_b128 v66, v[50:53] offset:36864
	s_or_b64 exec, exec, s[36:37]
	v_pk_fma_f32 v[50:51], v[32:33], v[64:65], v[36:37]
	v_pk_fma_f32 v[52:53], v[30:31], v[62:63], v[34:35]
	v_pk_fma_f32 v[50:51], v[28:29], v[60:61], v[50:51]
	v_pk_fma_f32 v[52:53], v[26:27], v[58:59], v[52:53]
	v_pk_fma_f32 v[50:51], v[24:25], v[40:41], v[50:51]
	v_pk_fma_f32 v[62:63], v[22:23], v[38:39], v[52:53]
	v_pk_fma_f32 v[52:53], v[20:21], v[48:49], v[50:51]
	v_pk_fma_f32 v[50:51], v[18:19], v[46:47], v[62:63]
	v_cvt_pk_bf16_f32 v63, v52, v53
	s_nop 0
	v_cvt_pk_bf16_f32 v62, v50, v51
	ds_write_b64 v176, v[62:63] offset:576
	s_and_saveexec_b64 s[36:37], s[8:9]
	v_add_u32_e32 v62, v137, v152
	ds_write_b128 v62, v[50:53] offset:36864
	s_or_b64 exec, exec, s[36:37]
	v_pk_fma_f32 v[50:51], v[32:33], v[60:61], v[36:37]
	v_pk_fma_f32 v[52:53], v[30:31], v[58:59], v[34:35]
	v_pk_fma_f32 v[50:51], v[28:29], v[40:41], v[50:51]
	v_pk_fma_f32 v[52:53], v[26:27], v[38:39], v[52:53]
	v_pk_fma_f32 v[50:51], v[24:25], v[48:49], v[50:51]
	v_pk_fma_f32 v[58:59], v[22:23], v[46:47], v[52:53]
	v_pk_fma_f32 v[52:53], v[20:21], v[44:45], v[50:51]
	v_pk_fma_f32 v[50:51], v[18:19], v[42:43], v[58:59]
	v_cvt_pk_bf16_f32 v59, v52, v53
	s_nop 0
	v_cvt_pk_bf16_f32 v58, v50, v51
	ds_write_b64 v176, v[58:59] offset:720
	s_and_saveexec_b64 s[36:37], s[8:9]
	v_add_u32_e32 v58, v137, v153
	ds_write_b128 v58, v[50:53] offset:36864
	s_or_b64 exec, exec, s[36:37]
	v_pk_fma_f32 v[40:41], v[32:33], v[40:41], v[36:37]
	v_pk_fma_f32 v[38:39], v[30:31], v[38:39], v[34:35]
	v_pk_fma_f32 v[40:41], v[28:29], v[48:49], v[40:41]
	v_pk_fma_f32 v[38:39], v[26:27], v[46:47], v[38:39]
	v_pk_fma_f32 v[40:41], v[24:25], v[44:45], v[40:41]
	v_pk_fma_f32 v[38:39], v[22:23], v[42:43], v[38:39]
	v_pk_fma_f32 v[40:41], v[20:21], v[56:57], v[40:41]
	v_pk_fma_f32 v[38:39], v[18:19], v[54:55], v[38:39]
	v_cvt_pk_bf16_f32 v43, v40, v41
	s_nop 0
	v_cvt_pk_bf16_f32 v42, v38, v39
	ds_write_b64 v176, v[42:43] offset:864
	s_and_saveexec_b64 s[36:37], s[8:9]
	v_add_u32_e32 v42, v137, v154
	ds_write_b128 v42, v[38:41] offset:36864
	s_or_b64 exec, exec, s[36:37]
	v_add_u32_e32 v186, 0x9000, v155
	v_add_u32_e32 v183, 0xd000, v155
	v_add_u32_e32 v184, 0x9000, v161
	v_add_u32_e32 v185, 0xd000, v161
	s_waitcnt lgkmcnt(0)
	s_barrier
; #define LAS __attribute__((address_space(3)))
; __device__ __forceinline__ float fexp(float x) { return __builtin_amdgcn_exp2f(x * 1.44269504089f); }
; __device__ __forceinline__ float fsigmoid(float x) { return __builtin_amdgcn_rcpf(1.0f + fexp(-x)); }
; __device__ __forceinline__ void lru_item(const Args& a, LAS unsigned char* lds, bool sample, int b, int head, int q, int tid, int lane, int wave) {
;     ...
; #pragma unroll
;             for (int tt = 0; tt < 2; ++tt) {
;                 const int tile = 2 * wave + tt;
;                 f32x4 ar = (f32x4){0.f, 0.f, 0.f, 0.f}, ax = ar;
; #pragma unroll
;                 for (int ks = 0; ks < 2; ++ks) {
;                     const bf16x8 af = *(const LAS bf16x8*)(XC + (16 * tile + fr) * XC_PITCH + 64 * ks + 16 * fq);
;                     ar = __builtin_amdgcn_mfma_f32_16x16x32_bf16(af, Bf[0][ks], ar, 0, 0, 0);
;                     ax = __builtin_amdgcn_mfma_f32_16x16x32_bf16(af, Bf[1][ks], ax, 0, 0, 0);
;                 }
; #pragma unroll
;                 for (int r4 = 0; r4 < 4; ++r4) {
;                     const int rr = 16 * tile + 4 * fq + r4;
;                     const float xcv = XCF[rr * 16 + fr];
;                     const float rg_ = fsigmoid(ar[r4] + ba), ig = fsigmoid(ax[r4] + bx_);
;                     const float la = -8.0f * rg_ * spl;
;                     const float av = fexp(la); AA[rr * 16 + fr] = av; BX[rr * 16 + fr] = __builtin_amdgcn_sqrtf(fmaxf(fmaf(-av, av, 1.0f), 0.f)) * (ig * xcv);
;                 }
;             }
	ds_read_b128 v[118:121], v177
	ds_read_b32 v108, v155 offset:36992
	ds_read_b128 v[126:129], v177 offset:64
	s_waitcnt lgkmcnt(2)
	v_mfma_f32_16x16x32_bf16 v[122:125], v[118:121], v[2:5], 0
	v_mov_b32_e32 v187, v140
	s_waitcnt lgkmcnt(0)
	v_mfma_f32_16x16x32_bf16 v[122:125], v[126:129], v[14:17], v[122:125]
	v_mfma_f32_16x16x32_bf16 v[118:121], v[118:121], v[6:9], 0
	s_nop 6
	v_add_f32_e32 v122, v97, v122
	v_mul_f32_e32 v122, 0xbfb8aa3b, v122
	v_exp_f32_e32 v122, v122
	v_mfma_f32_16x16x32_bf16 v[118:121], v[126:129], v[10:13], v[118:121]
	ds_read2_b32 v[126:127], v186 offset1:16
	v_add_f32_e32 v123, v97, v123
	v_add_f32_e32 v122, 1.0, v122
	v_rcp_f32_e32 v122, v122
	v_mul_f32_e32 v123, 0xbfb8aa3b, v123
	s_nop 2
	v_add_f32_e32 v118, v93, v118
	v_mul_f32_e32 v118, 0xbfb8aa3b, v118
	v_mul_f32_e32 v122, 0xc1000000, v122
	global_load_dwordx4 v[66:69], v[224:225], off
	v_lshl_add_u64 v[224:225], v[224:225], 0, v[228:229]
	v_mul_f32_e32 v122, v180, v122
	v_mul_f32_e32 v122, 0x3fb8aa3b, v122
	v_exp_f32_e32 v118, v118
	v_exp_f32_e32 v122, v122
	v_exp_f32_e32 v123, v123
	v_add_f32_e32 v119, v93, v119
	v_add_f32_e32 v118, 1.0, v118
	v_fma_f32 v128, -v122, v122, 1.0
	v_rcp_f32_e32 v118, v118
	v_max_f32_e32 v128, 0, v128
	v_sqrt_f32_e32 v128, v128
	v_mul_f32_e32 v119, 0xbfb8aa3b, v119
	s_waitcnt lgkmcnt(0)
	v_mul_f32_e32 v118, v126, v118
	v_exp_f32_e32 v119, v119
	v_mul_f32_e32 v118, v118, v128
	ds_write_b32 v156, v118
	v_add_f32_e32 v118, 1.0, v123
	v_rcp_f32_e32 v118, v118
	v_add_f32_e32 v124, v97, v124
	v_add_f32_e32 v119, 1.0, v119
	v_mul_f32_e32 v124, 0xbfb8aa3b, v124
	global_load_dwordx4 v[62:65], v[224:225], off
	v_lshl_add_u64 v[224:225], v[224:225], 0, v[228:229]
	v_mul_f32_e32 v118, 0xc1000000, v118
	v_mul_f32_e32 v118, v180, v118
	v_mul_f32_e32 v118, 0x3fb8aa3b, v118
	v_exp_f32_e32 v118, v118
	v_rcp_f32_e32 v119, v119
	v_exp_f32_e32 v124, v124
	v_add_f32_e32 v120, v93, v120
	v_fma_f32 v123, -v118, v118, 1.0
	ds_write2_b32 v183, v122, v118 offset1:16
	v_mul_f32_e32 v118, v127, v119
	v_add_f32_e32 v119, 1.0, v124
	v_rcp_f32_e32 v119, v119
	v_max_f32_e32 v123, 0, v123
	v_sqrt_f32_e32 v123, v123
	v_mul_f32_e32 v120, 0xbfb8aa3b, v120
	v_mul_f32_e32 v119, 0xc1000000, v119
	v_mul_f32_e32 v119, v180, v119
	v_mul_f32_e32 v119, 0x3fb8aa3b, v119
	v_exp_f32_e32 v120, v120
	v_exp_f32_e32 v119, v119
	v_mul_f32_e32 v118, v118, v123
	ds_write_b32 v157, v118
	global_load_dwordx4 v[58:61], v[224:225], off
	v_lshl_add_u64 v[224:225], v[224:225], 0, v[228:229]
	v_add_f32_e32 v118, 1.0, v120
	ds_write_b32 v155, v119 offset:53376
	v_fma_f32 v119, -v119, v119, 1.0
	v_rcp_f32_e32 v118, v118
	v_max_f32_e32 v119, 0, v119
	v_add_f32_e32 v120, v97, v125
	v_sqrt_f32_e32 v119, v119
	v_mul_f32_e32 v120, 0xbfb8aa3b, v120
	v_exp_f32_e32 v120, v120
	v_mul_f32_e32 v108, v118, v108
	v_mul_f32_e32 v108, v108, v119
	ds_write_b32 v158, v108
	v_add_f32_e32 v108, 1.0, v120
	v_rcp_f32_e32 v108, v108
	v_add_f32_e32 v118, v93, v121
	v_mul_f32_e32 v118, 0xbfb8aa3b, v118
	v_exp_f32_e32 v118, v118
	v_mul_f32_e32 v108, 0xc1000000, v108
	v_mul_f32_e32 v108, v180, v108
	v_mul_f32_e32 v108, 0x3fb8aa3b, v108
	v_exp_f32_e32 v108, v108
	ds_read_b32 v119, v159 offset:36864
	global_load_dwordx4 v[38:41], v[224:225], off
	v_lshl_add_u64 v[224:225], v[224:225], 0, v[228:229]
	v_add_f32_e32 v118, 1.0, v118
	v_rcp_f32_e32 v118, v118
	v_fma_f32 v120, -v108, v108, 1.0
	v_max_f32_e32 v120, 0, v120
	v_sqrt_f32_e32 v120, v120
	ds_write_b32 v159, v108 offset:53248
	s_waitcnt lgkmcnt(1)
	v_mul_f32_e32 v108, v118, v119
	v_mul_f32_e32 v108, v108, v120
	ds_write_b32 v160, v108
	ds_read_b128 v[118:121], v178
	ds_read_b32 v108, v161 offset:36992
	ds_read_b128 v[126:129], v178 offset:64
	s_waitcnt lgkmcnt(2)
	v_mfma_f32_16x16x32_bf16 v[122:125], v[118:121], v[2:5], 0
	s_waitcnt lgkmcnt(0)
	v_mfma_f32_16x16x32_bf16 v[122:125], v[126:129], v[14:17], v[122:125]
	v_mfma_f32_16x16x32_bf16 v[118:121], v[118:121], v[6:9], 0
	s_nop 6
	v_add_f32_e32 v122, v97, v122
	v_mul_f32_e32 v122, 0xbfb8aa3b, v122
	v_exp_f32_e32 v122, v122
	global_load_dwordx4 v[46:49], v[224:225], off
	v_lshl_add_u64 v[224:225], v[224:225], 0, v[228:229]
	v_mfma_f32_16x16x32_bf16 v[118:121], v[126:129], v[10:13], v[118:121]
	ds_read2_b32 v[126:127], v184 offset1:16
	v_add_f32_e32 v123, v97, v123
	v_add_f32_e32 v122, 1.0, v122
	v_rcp_f32_e32 v122, v122
	v_mul_f32_e32 v123, 0xbfb8aa3b, v123
	s_nop 2
	v_add_f32_e32 v118, v93, v118
	v_mul_f32_e32 v118, 0xbfb8aa3b, v118
	v_mul_f32_e32 v122, 0xc1000000, v122
	v_mul_f32_e32 v122, v180, v122
	v_mul_f32_e32 v122, 0x3fb8aa3b, v122
	v_exp_f32_e32 v118, v118
	v_exp_f32_e32 v122, v122
	v_exp_f32_e32 v123, v123
	v_add_f32_e32 v119, v93, v119
	v_add_f32_e32 v118, 1.0, v118
	v_fma_f32 v128, -v122, v122, 1.0
	v_rcp_f32_e32 v118, v118
	v_max_f32_e32 v128, 0, v128
	v_sqrt_f32_e32 v128, v128
	v_mul_f32_e32 v119, 0xbfb8aa3b, v119
	global_load_dwordx4 v[42:45], v[224:225], off
	v_lshl_add_u64 v[224:225], v[224:225], 0, v[228:229]
	s_waitcnt lgkmcnt(0)
; #define LAS __attribute__((address_space(3)))
; __device__ __forceinline__ float fexp(float x) { return __builtin_amdgcn_exp2f(x * 1.44269504089f); }
; __device__ __forceinline__ float fsigmoid(float x) { return __builtin_amdgcn_rcpf(1.0f + fexp(-x)); }
; __device__ __forceinline__ void lru_item(const Args& a, LAS unsigned char* lds, bool sample, int b, int head, int q, int tid, int lane, int wave) {
;     ...
; #pragma unroll
;                 for (int r4 = 0; r4 < 4; ++r4) {
;                     const int rr = 16 * tile + 4 * fq + r4;
;                     const float xcv = XCF[rr * 16 + fr];
;                     const float rg_ = fsigmoid(ar[r4] + ba), ig = fsigmoid(ax[r4] + bx_);
;                     const float la = -8.0f * rg_ * spl;
;                     const float av = fexp(la); AA[rr * 16 + fr] = av; BX[rr * 16 + fr] = __builtin_amdgcn_sqrtf(fmaxf(fmaf(-av, av, 1.0f), 0.f)) * (ig * xcv);
;                 }
;             }
;             __syncthreads();
;             const int sn = tid & 15, sg = tid >> 4;
;             float av[8], bv[8];
;             const LAS float* ap = AA + (8 * sg) * 16 + sn; LAS float* bp = BX + (8 * sg) * 16 + sn;
;             asm volatile("" : "+v"(ap), "+v"(bp));
;             { float P = 1.f, h = 0.f;
; #pragma unroll
;               for (int i = 0; i < 8; ++i) { av[i] = ap[i * 16]; bv[i] = bp[i * 16]; }
; #pragma unroll
;               for (int i = 0; i < 8; ++i) { h = av[i] * h + bv[i]; P *= av[i]; }
;               SEGP[tid] = P; SEGH[tid] = h; }
	v_mul_f32_e32 v118, v126, v118
	v_exp_f32_e32 v119, v119
	v_mul_f32_e32 v118, v118, v128
	ds_write_b32 v164, v118
	v_add_f32_e32 v118, 1.0, v123
	v_rcp_f32_e32 v118, v118
	v_add_f32_e32 v124, v97, v124
	v_add_f32_e32 v119, 1.0, v119
	v_mul_f32_e32 v124, 0xbfb8aa3b, v124
	v_mul_f32_e32 v118, 0xc1000000, v118
	v_mul_f32_e32 v118, v180, v118
	v_mul_f32_e32 v118, 0x3fb8aa3b, v118
	v_exp_f32_e32 v118, v118
	v_rcp_f32_e32 v119, v119
	v_exp_f32_e32 v124, v124
	v_add_f32_e32 v120, v93, v120
	v_fma_f32 v123, -v118, v118, 1.0
	ds_write2_b32 v185, v122, v118 offset1:16
	v_mul_f32_e32 v118, v127, v119
	v_add_f32_e32 v119, 1.0, v124
	v_rcp_f32_e32 v119, v119
	global_load_dwordx4 v[54:57], v[224:225], off
	v_max_f32_e32 v123, 0, v123
	v_sqrt_f32_e32 v123, v123
	v_mul_f32_e32 v120, 0xbfb8aa3b, v120
	v_mul_f32_e32 v119, 0xc1000000, v119
	v_mul_f32_e32 v119, v180, v119
	v_mul_f32_e32 v119, 0x3fb8aa3b, v119
	v_exp_f32_e32 v120, v120
	v_exp_f32_e32 v119, v119
	v_mul_f32_e32 v118, v118, v123
	ds_write_b32 v165, v118
	v_add_f32_e32 v118, 1.0, v120
	ds_write_b32 v161, v119 offset:53376
	v_fma_f32 v119, -v119, v119, 1.0
	v_rcp_f32_e32 v118, v118
	v_max_f32_e32 v119, 0, v119
	v_add_f32_e32 v120, v97, v125
	v_sqrt_f32_e32 v119, v119
	v_mul_f32_e32 v120, 0xbfb8aa3b, v120
	v_exp_f32_e32 v120, v120
	v_mul_f32_e32 v108, v118, v108
	v_mul_f32_e32 v108, v108, v119
	ds_write_b32 v166, v108
	v_add_u32_e32 v226, s30, v181
	v_ashrrev_i32_e32 v227, 31, v226
	v_lshlrev_b64 v[226:227], 11, v[226:227]
	v_lshl_add_u64 v[226:227], v[112:113], 0, v[226:227]
	global_load_dwordx4 v[50:53], v[226:227], off
	v_add_f32_e32 v108, 1.0, v120
	v_rcp_f32_e32 v108, v108
	v_add_f32_e32 v118, v93, v121
	v_mul_f32_e32 v118, 0xbfb8aa3b, v118
	v_exp_f32_e32 v118, v118
	v_mul_f32_e32 v108, 0xc1000000, v108
	v_mul_f32_e32 v108, v180, v108
	v_mul_f32_e32 v108, 0x3fb8aa3b, v108
	v_exp_f32_e32 v108, v108
	ds_read_b32 v119, v167 offset:36864
	v_add_f32_e32 v118, 1.0, v118
	v_rcp_f32_e32 v118, v118
	v_fma_f32 v120, -v108, v108, 1.0
	v_max_f32_e32 v120, 0, v120
	v_sqrt_f32_e32 v120, v120
	ds_write_b32 v167, v108 offset:53248
	s_waitcnt lgkmcnt(1)
	v_mul_f32_e32 v108, v118, v119
	v_mul_f32_e32 v108, v108, v120
	ds_write_b32 v168, v108
	v_mov_b32_e32 v108, v139
	s_waitcnt lgkmcnt(0)
	s_barrier
	ds_read2_b32 v[132:133], v108 offset1:16
	ds_read2_b32 v[130:131], v187 offset1:16
	ds_read2_b32 v[128:129], v108 offset0:32 offset1:48
	ds_read2_b32 v[126:127], v187 offset0:32 offset1:48
	ds_read2_b32 v[124:125], v108 offset0:64 offset1:80
	ds_read2_b32 v[122:123], v187 offset0:64 offset1:80
	ds_read2_b32 v[118:119], v108 offset0:96 offset1:112
	ds_read2_b32 v[120:121], v187 offset0:96 offset1:112
	s_waitcnt lgkmcnt(6)
	v_fma_f32 v108, 0, v132, v130
	v_mul_f32_e32 v188, v132, v133
	v_fma_f32 v108, v108, v133, v131
	s_waitcnt lgkmcnt(5)
	v_mul_f32_e32 v188, v188, v128
	s_waitcnt lgkmcnt(4)
	v_fma_f32 v108, v108, v128, v126
	v_mul_f32_e32 v188, v188, v129
	v_fma_f32 v108, v108, v129, v127
	s_waitcnt lgkmcnt(3)
	v_mul_f32_e32 v188, v188, v124
	s_waitcnt lgkmcnt(2)
	v_fma_f32 v108, v108, v124, v122
	v_mul_f32_e32 v188, v188, v125
	v_fma_f32 v108, v108, v125, v123
	s_waitcnt lgkmcnt(1)
	v_mul_f32_e32 v188, v188, v118
	s_waitcnt lgkmcnt(0)
	v_fma_f32 v108, v108, v118, v120
	v_mul_f32_e32 v188, v188, v119
	v_fma_f32 v108, v108, v119, v121
	ds_write_b32 v141, v188
	ds_write_b32 v142, v108
	s_waitcnt lgkmcnt(0)
	s_barrier
	s_and_saveexec_b64 s[36:37], s[18:19]
	s_cbranch_execz .LBB0_690
; #define LAS __attribute__((address_space(3)))
; __device__ __forceinline__ void lru_item(const Args& a, LAS unsigned char* lds, bool sample, int b, int head, int q, int tid, int lane, int wave) {
;     ...
;             if (wave == 0 && lane < 16) {
;                 const LAS float* pp = SEGP + lane; const LAS float* hp = SEGH + lane; LAS float* cp = CAR + lane;
;                 asm volatile("" : "+v"(pp), "+v"(hp), "+v"(cp));
;                 float run = hcar;
; #pragma unroll
;                 for (int h2 = 0; h2 < 2; ++h2) {
;                     float sp_[16], sh_[16];
; #pragma unroll
;                     for (int s2 = 0; s2 < 16; ++s2) { sp_[s2] = pp[(16 * h2 + s2) * 16]; sh_[s2] = hp[(16 * h2 + s2) * 16]; }
; #pragma unroll
;                     for (int s2 = 0; s2 < 16; ++s2) { cp[(16 * h2 + s2) * 16] = run; run = sp_[s2] * run + sh_[s2]; }
;                 }
;                 hcar = run;
	v_mov_b32_e32 v108, v144
	v_mov_b32_e32 v211, v143
	v_mov_b32_e32 v222, v145
	ds_read2_b32 v[188:189], v211 offset1:16
	ds_read2_b32 v[190:191], v108 offset1:16
	ds_read2_b32 v[192:193], v211 offset0:32 offset1:48
	ds_read2_b32 v[194:195], v108 offset0:32 offset1:48
	ds_read2_b32 v[196:197], v211 offset0:64 offset1:80
	ds_read2_b32 v[198:199], v108 offset0:64 offset1:80
	ds_read2_b32 v[200:201], v211 offset0:96 offset1:112
	ds_read2_b32 v[202:203], v108 offset0:96 offset1:112
	ds_read2_b32 v[204:205], v211 offset0:128 offset1:144
	ds_read2_b32 v[206:207], v108 offset0:128 offset1:144
	ds_read2_b32 v[208:209], v211 offset0:160 offset1:176
	ds_read2_b32 v[212:213], v108 offset0:160 offset1:176
	ds_read2_b32 v[214:215], v211 offset0:192 offset1:208
	ds_read2_b32 v[216:217], v108 offset0:192 offset1:208
	ds_read2_b32 v[218:219], v211 offset0:224 offset1:240
	ds_read2_b32 v[220:221], v108 offset0:224 offset1:240
	s_waitcnt lgkmcnt(14)
	v_fma_f32 v188, v109, v188, v190
	v_fmac_f32_e32 v191, v188, v189
	ds_write2_b32 v222, v109, v188 offset1:16
	s_waitcnt lgkmcnt(13)
	v_fma_f32 v109, v191, v192, v194
	v_fmac_f32_e32 v195, v109, v193
	ds_write2_b32 v222, v191, v109 offset0:32 offset1:48
	s_waitcnt lgkmcnt(12)
	v_fma_f32 v109, v195, v196, v198
	v_fmac_f32_e32 v199, v109, v197
	ds_write2_b32 v222, v195, v109 offset0:64 offset1:80
	s_waitcnt lgkmcnt(11)
	v_fma_f32 v109, v199, v200, v202
	v_fmac_f32_e32 v203, v109, v201
	ds_write2_b32 v222, v199, v109 offset0:96 offset1:112
	s_waitcnt lgkmcnt(10)
	v_fma_f32 v109, v203, v204, v206
	v_fmac_f32_e32 v207, v109, v205
	ds_write2_b32 v222, v203, v109 offset0:128 offset1:144
	s_waitcnt lgkmcnt(9)
	v_fma_f32 v109, v207, v208, v212
	v_fmac_f32_e32 v213, v109, v209
	ds_write2_b32 v222, v207, v109 offset0:160 offset1:176
	s_waitcnt lgkmcnt(8)
	v_fma_f32 v109, v213, v214, v216
	v_fmac_f32_e32 v217, v109, v215
	ds_write2_b32 v222, v213, v109 offset0:192 offset1:208
	s_waitcnt lgkmcnt(7)
	v_fma_f32 v109, v217, v218, v220
	ds_write2_b32 v222, v217, v109 offset0:224 offset1:240
	v_fmac_f32_e32 v221, v109, v219
	v_add_u32_e32 v109, 0x400, v211
	ds_read2_b32 v[188:189], v109 offset1:16
	v_add_u32_e32 v108, 0x400, v108
	ds_read2_b32 v[190:191], v108 offset1:16
	ds_read2_b32 v[192:193], v109 offset0:32 offset1:48
	ds_read2_b32 v[194:195], v108 offset0:32 offset1:48
	ds_read2_b32 v[196:197], v109 offset0:64 offset1:80
	ds_read2_b32 v[198:199], v108 offset0:64 offset1:80
	ds_read2_b32 v[200:201], v109 offset0:96 offset1:112
	ds_read2_b32 v[202:203], v108 offset0:96 offset1:112
	ds_read2_b32 v[204:205], v109 offset0:128 offset1:144
	ds_read2_b32 v[206:207], v108 offset0:128 offset1:144
	ds_read2_b32 v[208:209], v109 offset0:160 offset1:176
	ds_read2_b32 v[212:213], v108 offset0:160 offset1:176
	ds_read2_b32 v[214:215], v109 offset0:192 offset1:208
	ds_read2_b32 v[216:217], v108 offset0:192 offset1:208
	ds_read2_b32 v[218:219], v109 offset0:224 offset1:240
	ds_read2_b32 v[108:109], v108 offset0:224 offset1:240
	s_waitcnt lgkmcnt(14)
	v_fma_f32 v188, v221, v188, v190
	v_add_u32_e32 v190, 0x400, v222
	v_fmac_f32_e32 v191, v188, v189
	ds_write2_b32 v190, v221, v188 offset1:16
	s_waitcnt lgkmcnt(13)
	v_fma_f32 v188, v191, v192, v194
	v_fmac_f32_e32 v195, v188, v193
	ds_write2_b32 v190, v191, v188 offset0:32 offset1:48
	s_waitcnt lgkmcnt(12)
	v_fma_f32 v188, v195, v196, v198
	v_fmac_f32_e32 v199, v188, v197
	ds_write2_b32 v190, v195, v188 offset0:64 offset1:80
	s_waitcnt lgkmcnt(11)
	v_fma_f32 v188, v199, v200, v202
	v_fmac_f32_e32 v203, v188, v201
	ds_write2_b32 v190, v199, v188 offset0:96 offset1:112
	s_waitcnt lgkmcnt(10)
	v_fma_f32 v188, v203, v204, v206
	v_fmac_f32_e32 v207, v188, v205
	ds_write2_b32 v190, v203, v188 offset0:128 offset1:144
	s_waitcnt lgkmcnt(9)
	v_fma_f32 v188, v207, v208, v212
	v_fmac_f32_e32 v213, v188, v209
	ds_write2_b32 v190, v207, v188 offset0:160 offset1:176
	s_waitcnt lgkmcnt(8)
	v_fma_f32 v188, v213, v214, v216
	v_fmac_f32_e32 v217, v188, v215
	s_waitcnt lgkmcnt(6)
	v_fma_f32 v108, v217, v218, v108
	v_fmac_f32_e32 v109, v108, v219
	ds_write2_b32 v190, v213, v188 offset0:192 offset1:208
	ds_write2_b32 v190, v217, v108 offset0:224 offset1:240
